# same up-front LDS reads with counted waits applied to the two cross-chunk carry loops of the qkv-phase scans
# speedup vs baseline: 1.0055x; 1.0014x over previous
.LBB0_596:
	v_add_u32_e32 v70, s22, v166
	ds_read2st64_b32 v[66:67], v70 offset0:12 offset1:14
	ds_read2st64_b32 v[68:69], v70 offset0:76 offset1:78
	ds_read2st64_b32 v[218:219], v70 offset0:8 offset1:10
	ds_read2st64_b32 v[220:221], v70 offset0:72 offset1:74
	ds_read2st64_b32 v[222:223], v70 offset0:4 offset1:6
	ds_read2st64_b32 v[224:225], v70 offset0:68 offset1:70
	ds_read2st64_b32 v[226:227], v70 offset1:2
	ds_read2st64_b32 v[228:229], v70 offset0:64 offset1:66
	s_addk_i32 s22, 0xf000
	s_cmpk_lg_i32 s22, 0x1200
	s_waitcnt lgkmcnt(6)
	v_mul_f32_e32 v65, v65, v67
	v_fma_f32 v64, v64, v67, v69
	v_fmac_f32_e32 v68, v64, v66
	v_mul_f32_e32 v69, v65, v66
	s_waitcnt lgkmcnt(4)
	v_fma_f32 v221, v68, v219, v221
	v_mul_f32_e32 v219, v69, v219
	v_fmac_f32_e32 v220, v221, v218
	v_mul_f32_e32 v221, v219, v218
	s_waitcnt lgkmcnt(2)
	v_fma_f32 v225, v220, v223, v225
	v_mul_f32_e32 v223, v221, v223
	v_fmac_f32_e32 v224, v225, v222
	v_mul_f32_e32 v225, v223, v222
	s_waitcnt lgkmcnt(0)
	v_fma_f32 v229, v224, v227, v229
	v_mul_f32_e32 v227, v225, v227
	v_fmac_f32_e32 v228, v229, v226
	v_mul_f32_e32 v65, v227, v226
	v_mov_b32_e32 v64, v228
	s_cbranch_scc1 .LBB0_596
	s_mov_b64 s[22:23], 0

.LBB0_600:
	v_add_u32_e32 v70, s22, v167
	ds_read2st64_b32 v[64:65], v70 offset1:2
	ds_read2st64_b32 v[66:67], v70 offset0:64 offset1:66
	ds_read2st64_b32 v[218:219], v70 offset0:4 offset1:6
	ds_read2st64_b32 v[68:69], v70 offset0:68 offset1:70
	ds_read2st64_b32 v[220:221], v70 offset0:8 offset1:10
	ds_read2st64_b32 v[222:223], v70 offset0:72 offset1:74
	ds_read2st64_b32 v[224:225], v70 offset0:12 offset1:14
	ds_read2st64_b32 v[226:227], v70 offset0:76 offset1:78
	s_addk_i32 s22, 0x1000
	s_cmpk_eq_i32 s22, 0x4000
	s_waitcnt lgkmcnt(6)
	v_fma_f32 v66, v91, v64, v66
	v_mul_f32_e32 v64, v90, v64
	v_fmac_f32_e32 v67, v66, v65
	v_mul_f32_e32 v66, v64, v65
	s_waitcnt lgkmcnt(4)
	v_fma_f32 v67, v67, v218, v68
	v_mul_f32_e32 v218, v66, v218
	v_fmac_f32_e32 v69, v67, v219
	v_mul_f32_e32 v68, v218, v219
	s_waitcnt lgkmcnt(2)
	v_fma_f32 v222, v69, v220, v222
	v_mul_f32_e32 v220, v68, v220
	v_fmac_f32_e32 v223, v222, v221
	v_mul_f32_e32 v222, v220, v221
	s_waitcnt lgkmcnt(0)
	v_fma_f32 v226, v223, v224, v226
	v_mul_f32_e32 v224, v222, v224
	v_fmac_f32_e32 v227, v226, v225
	v_mul_f32_e32 v90, v224, v225
	v_mov_b32_e32 v91, v227
	s_cbranch_scc0 .LBB0_600
	v_mov_b32_e32 v64, v91
	v_mov_b32_e32 v65, v90
	s_branch .LBB0_553
